# nsa_closed_form_masks_and_item_index_prefetch
# speedup vs baseline: 1.0249x; 1.0076x over previous
.LBB0_421:
	s_add_i32 s0, 0, 0x22ff0
	v_writelane_b32 v254, s0, 7
	s_waitcnt vmcnt(2)
	v_mov_b32_e32 v91, s0
	s_add_i32 s0, 0, 0x19c00
	v_writelane_b32 v254, s0, 8
	s_add_i32 s0, 0, 0x1bc00
	v_writelane_b32 v254, s0, 9
	v_writelane_b32 v254, s86, 10
	v_cmp_eq_u32_e64 s[8:9], 0, v113
	s_add_i32 s65, 0, 0x11c00
	v_writelane_b32 v254, s87, 11
	v_writelane_b32 v254, s88, 12
	s_mov_b32 s43, 0
	v_mov_b32_e32 v77, 0
	v_writelane_b32 v254, s89, 13
	v_writelane_b32 v254, s90, 14
	s_movk_i32 s10, 0x90
	s_waitcnt vmcnt(1)
	v_mov_b32_e32 v92, 0xf149f2ca
	v_writelane_b32 v254, s91, 15
	v_writelane_b32 v254, s92, 16
	v_mbcnt_hi_u32_b32 v174, -1, v230
	v_mov_b32_e32 v93, 0x80
	v_writelane_b32 v254, s93, 17
	v_writelane_b32 v254, s85, 18
	v_writelane_b32 v254, s94, 19
	v_mov_b32_e32 v94, 0x100
	v_mov_b32_e32 v95, 0x200
	v_writelane_b32 v254, s95, 20
	v_writelane_b32 v254, s71, 21
	v_writelane_b32 v254, s72, 22
	v_writelane_b32 v254, s74, 23
	s_waitcnt vmcnt(0)
	v_mov_b32_e32 v96, 0x400
	v_mov_b32_e32 v97, 0x800
	v_writelane_b32 v254, s75, 24
	v_writelane_b32 v254, s96, 25
	v_writelane_b32 v254, s97, 26
	v_writelane_b32 v254, s66, 27
	v_mov_b32_e32 v98, 0x1000
	v_mov_b32_e32 v99, 0x2000
	v_writelane_b32 v254, s67, 28
	v_writelane_b32 v254, s8, 29
	v_mov_b32_e32 v100, 0x4000
	v_mov_b32_e32 v101, 0x8000
	v_writelane_b32 v254, s9, 30
	v_mov_b32_e32 v102, 0xff800000
	v_writelane_b32 v254, s65, 31
	s_mov_b32 s99, 0
	s_branch .LBB0_424

.LBB0_424:
	s_and_saveexec_b64 s[0:1], s[8:9]
	s_cbranch_execz .LBB0_428
	s_mov_b64 s[4:5], exec
	v_mbcnt_lo_u32_b32 v0, s4, 0
	v_mbcnt_hi_u32_b32 v0, s5, v0
	v_cmp_eq_u32_e32 vcc, 0, v0
	s_and_saveexec_b64 s[2:3], vcc
	s_cbranch_execz .LBB0_427
	s_bcnt1_i32_b64 s4, s[4:5]
	v_mov_b32_e32 v1, s4
	s_cmp_lg_u32 s99, 0
	s_cbranch_scc1 .Lnsa_item_pf
	global_atomic_add v1, v77, v1, s[46:47] sc0
	s_branch .LBB0_427
.Lnsa_item_pf:
	s_waitcnt vmcnt(0)
	v_mov_b32_e32 v1, v151

.LBB0_581:
	s_or_b64 exec, exec, s[2:3]
	v_cmp_eq_u32_e32 vcc, 0, v210
	s_and_saveexec_b64 s[100:101], vcc
	v_mov_b32_e32 v151, 1
	global_atomic_add v151, v77, v151, s[46:47] sc0
	s_mov_b64 exec, s[100:101]
	s_mov_b32 s99, 1
	s_lshl_b32 s0, s15, 3
	v_readlane_b32 s1, v254, 9
	v_mul_f32_e32 v32, 0xbfb8aa3b, v72
	s_add_i32 s0, s1, s0
	v_and_b32_e32 v33, 31, v75
	v_exp_f32_e32 v34, v32
	v_lshl_add_u32 v32, v88, 3, s0
	v_lshl_add_u32 v33, v33, 3, s1
	s_waitcnt lgkmcnt(0)
	s_barrier
	ds_read_b64 v[60:61], v32
	ds_read_b64 v[32:33], v33
	v_mul_f32_e32 v35, 0xbfb8aa3b, v74
	v_exp_f32_e32 v35, v35
	v_lshlrev_b64 v[68:69], 16, v[82:83]
	v_add_f32_e32 v34, 1.0, v34
	s_waitcnt lgkmcnt(0)
	ds_bpermute_b32 v40, v108, v33
	ds_bpermute_b32 v41, v108, v32
	v_add_f32_e32 v35, 1.0, v35
	v_rcp_f32_e32 v83, v35
	v_xor_b32_e32 v35, 8, v174
	v_cmp_lt_i32_e32 vcc, v35, v116
	s_waitcnt lgkmcnt(1)
	v_or_b32_e32 v33, v40, v33
	s_waitcnt lgkmcnt(0)
	v_or_b32_e32 v32, v41, v32
	v_cndmask_b32_e32 v35, v174, v35, vcc
	v_lshlrev_b32_e32 v35, 2, v35
	ds_bpermute_b32 v40, v35, v33
	ds_bpermute_b32 v35, v35, v32
	v_rcp_f32_e32 v34, v34
	s_lshr_b32 s55, s14, 6
	s_lshl_b64 s[0:1], 2, s55
	s_add_u32 s0, s0, -1
	s_waitcnt lgkmcnt(0)
	v_pk_fma_f32 v[74:75], v[34:35], v[28:29], 0 op_sel_hi:[0,1,0]
	v_xor_b32_e32 v28, 4, v174
	v_cmp_lt_i32_e32 vcc, v28, v116
	v_pk_fma_f32 v[58:59], v[34:35], v[26:27], 0 op_sel_hi:[0,1,0]
	v_or_b32_e32 v26, v40, v33
	v_cndmask_b32_e32 v28, v174, v28, vcc
	v_or_b32_e32 v27, v35, v32
	v_lshlrev_b32_e32 v28, 2, v28
	ds_bpermute_b32 v29, v28, v26
	ds_bpermute_b32 v28, v28, v27
	v_pk_fma_f32 v[64:65], v[34:35], v[20:21], 0 op_sel_hi:[0,1,0]
	v_pk_fma_f32 v[62:63], v[34:35], v[22:23], 0 op_sel_hi:[0,1,0]
	s_addc_u32 s1, s1, -1
	s_waitcnt lgkmcnt(1)
	v_or_b32_e32 v20, v29, v26
	s_waitcnt lgkmcnt(0)
	v_or_b32_e32 v21, v28, v27
	ds_bpermute_b32 v22, v37, v20
	ds_bpermute_b32 v23, v37, v21
	s_cmp_lg_u32 s55, 63
	v_pk_fma_f32 v[56:57], v[34:35], v[18:19], 0 op_sel_hi:[0,1,0]
	v_mul_f32_e32 v18, 0xbfb8aa3b, v73
	s_cselect_b32 s1, s1, -1
	s_cselect_b32 s0, s0, -1
	s_lshl_b32 s2, s10, 1
	v_exp_f32_e32 v18, v18
	s_waitcnt lgkmcnt(1)
	v_or_b32_e32 v19, v22, v20
	s_waitcnt lgkmcnt(0)
	v_or_b32_e32 v20, v23, v21
	s_add_u32 s58, s92, s2
	ds_bpermute_b32 v21, v36, v19
	ds_bpermute_b32 v22, v36, v20
	s_addc_u32 s59, s93, 0
	v_readlane_b32 s2, v253, 61
	v_readlane_b32 s3, v253, 62
	s_add_u32 s60, s2, s11
	v_readlane_b32 s2, v254, 32
	s_addc_u32 s61, s3, 0
	s_sub_i32 s2, 0xde0, s2
	v_pk_fma_f32 v[70:71], v[34:35], v[16:17], 0 op_sel_hi:[0,1,0]
	v_add_f32_e32 v16, 1.0, v18
	s_ashr_i32 s2, s2, 6
	v_mul_u32_u24_e32 v113, 0x90, v114
	v_rcp_f32_e32 v114, v16
	s_cmpk_gt_i32 s14, 0x1fe
	s_waitcnt lgkmcnt(1)
	v_or_b32_e32 v16, v21, v19
	s_waitcnt lgkmcnt(0)
	v_or_b32_e32 v17, v22, v20
	s_cselect_b32 s2, s2, 0
	v_and_b32_e32 v16, s1, v16
	v_and_b32_e32 v17, s0, v17
	s_lshl_b64 s[2:3], -1, s2
	v_add3_u32 v116, 0, v89, v76
	v_mul_u32_u24_e32 v110, 0x90, v110
	v_mul_u32_u24_e32 v111, 0x90, v111
	v_mul_u32_u24_e32 v112, 0x90, v112
	v_pk_fma_f32 v[66:67], v[34:35], v[30:31], 0 op_sel_hi:[0,1,0]
	v_pk_fma_f32 v[86:87], v[34:35], v[24:25], 0 op_sel_hi:[0,1,0]
	v_readfirstlane_b32 s56, v16
	v_readfirstlane_b32 s57, v17
	s_and_b64 s[34:35], s[0:1], s[2:3]
	v_lshl_add_u32 v117, v90, 1, v116
	s_add_i32 s62, s54, 0xfffffe03
	v_add_u32_e32 v118, 0xfffffe00, v78
	v_mul_u32_u24_e32 v119, 0x90, v38
	v_mul_u32_u24_e32 v120, 0x90, v39
	v_and_b32_e32 v211, 1, v210
	v_lshlrev_b32_e32 v211, 5, v211
	v_sub_u32_e32 v211, 16, v211
	v_lshrrev_b32_e32 v228, 1, v82
	v_xor_b32_e32 v228, v228, v82
	v_bfe_u32 v229, v228, 3, 1
	v_bfe_u32 v228, v228, 2, 1
	v_mad_i32_i24 v117, v229, v211, v117
	v_mad_i32_i24 v116, v228, v211, v116
	v_lshrrev_b32_e32 v228, 1, v210
	v_xor_b32_e32 v228, v228, v210
	v_bfe_u32 v228, v228, 2, 1
	v_lshlrev_b32_e32 v228, 4, v228
	v_xor_b32_e32 v208, v103, v228
	v_xor_b32_e32 v209, v115, v228
	v_add3_u32 v175, v110, v79, v208
	v_add3_u32 v211, v111, v79, v208
	v_add3_u32 v228, v112, v104, v208
	v_add3_u32 v229, v113, v104, v208
	v_add_u32_e32 v231, v209, v119
	v_add_u32_e32 v252, v209, v120
	s_mov_b64 s[36:37], 0
	s_mov_b64 s[38:39], -1
	s_branch .LBB0_583

.Lnsa_diag:
	v_lshrrev_b64 v[40:41], s4, v[60:61]
	v_and_b32_e32 v40, 1, v40
	v_cmp_eq_u32_e32 vcc, 1, v40
	v_mov_b32_e32 v127, 0
	s_and_saveexec_b64 s[0:1], vcc
	s_cbranch_execz .LBB0_592
	s_cmp_lt_u32 s4, s55
	v_mov_b32_e32 v127, 0xffff
	s_cbranch_scc1 .LBB0_592
	v_lshl_or_b32 v40, s4, 6, v84
	v_sub_u32_e32 v40, v78, v40
	v_add_u32_e32 v41, 1, v40
	v_add_u32_e32 v42, 0xffffffe1, v40
	v_med3_i32 v41, v41, 0, 8
	v_med3_i32 v42, v42, 0, 8
	v_bfm_b32 v41, v41, 0
	v_bfm_b32 v42, v42, 8
	v_or_b32_e32 v127, v41, v42

.LBB0_598:
	s_lshl_b32 s2, s4, 6
	s_or_b32 s0, s2, 63
	s_cmp_le_i32 s0, s54
	s_cselect_b64 s[0:1], -1, 0
	s_cmp_gt_i32 s2, s62
	s_cselect_b64 s[6:7], -1, 0
	s_and_b64 s[0:1], s[0:1], s[6:7]
	v_mov_b32_e32 v127, 0xffff
	s_and_b64 vcc, exec, s[0:1]
	s_cbranch_vccnz .Lnsa_fastq_all
	v_or_b32_e32 v40, s2, v84
	v_sub_u32_e32 v40, v78, v40
	v_add_u32_e32 v41, 1, v40
	v_add_u32_e32 v42, 0xffffffe1, v40
	v_add_u32_e32 v43, 0xfffffe01, v40
	v_add_u32_e32 v44, 0xfffffde1, v40
	v_med3_i32 v41, v41, 0, 8
	v_med3_i32 v42, v42, 0, 8
	v_med3_i32 v43, v43, 0, 8
	v_med3_i32 v44, v44, 0, 8
	v_bfm_b32 v41, v41, 0
	v_bfm_b32 v42, v42, 8
	v_bfm_b32 v43, v43, 0
	v_bfm_b32 v44, v44, 8
	v_or_b32_e32 v41, v41, v42
	v_or_b32_e32 v43, v43, v44
	v_not_b32_e32 v43, v43
	v_and_b32_e32 v127, v41, v43
